# v18 + P4 merge wave_sum via DPP/permlane swaps instead of 6 ds_bpermute round trips per value (bit-identical sums)
# speedup vs baseline: 1.0001x; 1.0001x over previous
; __global__ void __launch_bounds__(512, 2) fwd_megakernel(Params P) {
;     ...
;     for (int m = gw; m < T; m += 2 * NGW) {
;         float l[2][3]; u32x4 r0[2], r1[2], r2[2], rb_[2];
; #pragma unroll
;         for (int j = 0; j < 2; ++j) { const int mj = (m + j * NGW < T) ? m + j * NGW : m;
;             l[j][0] = LSE[(size_t)mj * 8 + h]; l[j][1] = LSE[(size_t)(T + mj) * 8 + h]; l[j][2] = LSE[(size_t)(2 * T + mj) * 8 + h];
;             r0[j] = *(const u32x4*)(OA + (size_t)mj * 512 + 8 * lane); r1[j] = *(const u32x4*)(OA + (size_t)(T + mj) * 512 + 8 * lane); r2[j] = *(const u32x4*)(OA + (size_t)(2 * T + mj) * 512 + 8 * lane);
;             rb_[j] = *(const u32x4*)(OB + (size_t)mj * 512 + 8 * lane); }
; #pragma unroll
;         for (int j = 0; j < 2; ++j) { const int mj = m + j * NGW;
;             const float mx = fmaxf(l[j][0], fmaxf(l[j][1], l[j][2])); float w0 = __expf(l[j][0] - mx), w1 = __expf(l[j][1] - mx), w2 = __expf(l[j][2] - mx); const float inv = 1.f / (w0 + w1 + w2); w0 *= inv; w1 *= inv; w2 *= inv;
;             float a0[8], a1[8], a2[8], ob[8], oa[8];
;             unpack8(r0[j], a0); unpack8(r1[j], a1); unpack8(r2[j], a2); unpack8(rb_[j], ob);
;             float sa = 0.f, sb = 0.f;
; #pragma unroll
;             for (int i = 0; i < 8; ++i) { oa[i] = w0 * a0[i] + w1 * a1[i] + w2 * a2[i]; sa += oa[i] * oa[i]; sb += ob[i] * ob[i]; }
;             const float ra = __builtin_amdgcn_rsqf(wave_sum(sa) * (1.f / 512.f) + EPS), rb = __builtin_amdgcn_rsqf(wave_sum(sb) * (1.f / 512.f) + EPS);
.LBB0_993:
	s_ashr_i32 s3, s2, 31
	s_lshl_b64 s[0:1], s[2:3], 5
	v_lshl_add_u64 v[20:21], v[24:25], 0, s[0:1]
	s_add_i32 s0, s2, 0x8000
	s_ashr_i32 s1, s0, 31
	s_lshl_b64 s[4:5], s[0:1], 5
	v_lshl_add_u64 v[22:23], v[24:25], 0, s[4:5]
	s_add_i32 s4, s2, 0x10000
	s_lshl_b64 s[6:7], s[2:3], 10
	s_ashr_i32 s5, s4, 31
	v_lshl_add_u64 v[16:17], v[28:29], 0, s[6:7]
	s_lshl_b64 s[10:11], s[4:5], 5
	s_lshl_b64 s[0:1], s[0:1], 10
	global_load_dwordx4 v[16:19], v[16:17], off
	v_lshl_add_u64 v[40:41], v[24:25], 0, s[10:11]
	global_load_dword v39, v[20:21], off
	global_load_dword v54, v[22:23], off
	global_load_dword v55, v[40:41], off
	v_lshl_add_u64 v[20:21], v[26:27], 0, s[0:1]
	s_lshl_b64 s[0:1], s[4:5], 10
	global_load_dwordx4 v[20:23], v[20:21], off
	v_lshl_add_u64 v[50:51], v[26:27], 0, s[0:1]
	v_lshl_add_u64 v[48:49], v[26:27], 0, s[6:7]
	global_load_dwordx4 v[40:43], v[50:51], off
	global_load_dwordx4 v[44:47], v[48:49], off
	s_add_i32 s4, s28, s2
	s_cmp_lt_i32 s4, 0x8000
	s_cselect_b32 s0, s4, s2
	s_ashr_i32 s1, s0, 31
	s_add_i32 s6, s0, 0x8000
	s_add_i32 s16, s0, 0x10000
	s_lshl_b64 s[10:11], s[0:1], 5
	s_ashr_i32 s7, s6, 31
	s_ashr_i32 s17, s16, 31
	s_lshl_b64 s[14:15], s[0:1], 10
	s_lshl_b64 s[0:1], s[6:7], 5
	s_lshl_b64 s[18:19], s[16:17], 5
	v_lshl_add_u64 v[48:49], v[24:25], 0, s[10:11]
	v_lshl_add_u64 v[50:51], v[24:25], 0, s[0:1]
	v_lshl_add_u64 v[52:53], v[24:25], 0, s[18:19]
	global_load_dword v56, v[48:49], off
	global_load_dword v57, v[50:51], off
	global_load_dword v58, v[52:53], off
	s_lshl_b64 s[10:11], s[16:17], 10
	s_waitcnt vmcnt(9)
	v_lshlrev_b32_e32 v61, 16, v18
	v_and_b32_e32 v62, 0xffff0000, v18
	s_waitcnt vmcnt(6)
	v_max3_f32 v48, v39, v54, v55
	v_sub_f32_e32 v39, v39, v48
	v_lshlrev_b32_e32 v63, 16, v19
	s_waitcnt vmcnt(5)
	v_lshlrev_b32_e32 v50, 16, v20
	v_and_b32_e32 v51, 0xffff0000, v20
	s_waitcnt vmcnt(4)
	v_lshlrev_b32_e32 v18, 16, v40
	v_and_b32_e32 v20, 0xffff0000, v40
	v_sub_f32_e32 v40, v54, v48
	v_and_b32_e32 v64, 0xffff0000, v19
	v_lshlrev_b32_e32 v65, 16, v21
	v_and_b32_e32 v66, 0xffff0000, v21
	s_waitcnt vmcnt(3)
	v_lshlrev_b32_e32 v19, 16, v44
	v_and_b32_e32 v21, 0xffff0000, v44
	v_sub_f32_e32 v44, v55, v48
	v_mul_f32_e32 v39, 0x3fb8aa3b, v39
	v_mul_f32_e32 v40, 0x3fb8aa3b, v40
	v_mul_f32_e32 v44, 0x3fb8aa3b, v44
	v_exp_f32_e32 v49, v39
	v_exp_f32_e32 v39, v40
	v_exp_f32_e32 v48, v44
	v_lshlrev_b32_e32 v67, 16, v22
	v_and_b32_e32 v68, 0xffff0000, v22
	v_add_f32_e32 v40, v49, v39
	v_add_f32_e32 v40, v48, v40
	v_div_scale_f32 v44, s[0:1], v40, v40, 1.0
	v_rcp_f32_e32 v54, v44
	v_div_scale_f32 v55, vcc, 1.0, v40, 1.0
	v_lshlrev_b32_e32 v69, 16, v23
	v_fma_f32 v72, -v44, v54, 1.0
	v_fmac_f32_e32 v54, v72, v54
	v_mul_f32_e32 v72, v55, v54
	v_fma_f32 v73, -v44, v72, v55
	v_fmac_f32_e32 v72, v73, v54
	v_fma_f32 v44, -v44, v72, v55
	v_div_fmas_f32 v44, v44, v54, v72
	v_div_fixup_f32 v40, v44, v40, 1.0
	v_pk_mul_f32 v[48:49], v[48:49], v[40:41] op_sel_hi:[1,0]
	v_mul_f32_e32 v39, v39, v40
	v_pk_mul_f32 v[18:19], v[48:49], v[18:19]
	v_pk_mul_f32 v[20:21], v[48:49], v[20:21]
	v_fma_f32 v19, v39, v50, v19
	v_add_f32_e32 v54, v18, v19
	v_and_b32_e32 v19, 0xffff0000, v45
	v_and_b32_e32 v18, 0xffff0000, v41
	v_pk_mul_f32 v[18:19], v[48:49], v[18:19]
	v_and_b32_e32 v70, 0xffff0000, v23
	v_fma_f32 v19, v39, v66, v19
	v_lshlrev_b32_e32 v22, 16, v41
	v_lshlrev_b32_e32 v23, 16, v45
	v_fma_f32 v21, v39, v51, v21
	v_add_f32_e32 v66, v18, v19
	v_lshlrev_b32_e32 v18, 16, v42
	v_lshlrev_b32_e32 v19, 16, v46
	v_and_b32_e32 v53, 0xffff0000, v16
	v_pk_mul_f32 v[22:23], v[48:49], v[22:23]
	v_add_f32_e32 v55, v20, v21
	v_pk_mul_f32 v[18:19], v[48:49], v[18:19]
	v_lshlrev_b32_e32 v52, 16, v16
	v_lshlrev_b32_e32 v59, 16, v17
	v_and_b32_e32 v60, 0xffff0000, v17
	v_mul_f32_e32 v71, v53, v53
	v_lshlrev_b32_e32 v16, 16, v43
	v_lshlrev_b32_e32 v17, 16, v47
	v_fma_f32 v23, v39, v65, v23
	v_mul_f32_e32 v20, v55, v55
	v_fma_f32 v19, v39, v67, v19
	v_fmac_f32_e32 v71, v52, v52
	v_add_f32_e32 v65, v22, v23
	v_fmac_f32_e32 v20, v54, v54
	v_add_f32_e32 v67, v18, v19
	v_and_b32_e32 v19, 0xffff0000, v46
	v_and_b32_e32 v18, 0xffff0000, v42
	v_pk_mul_f32 v[16:17], v[48:49], v[16:17]
	v_fmac_f32_e32 v71, v59, v59
	v_fmac_f32_e32 v20, v65, v65
	v_pk_mul_f32 v[18:19], v[48:49], v[18:19]
	v_fma_f32 v17, v39, v69, v17
	v_fmac_f32_e32 v71, v60, v60
	v_fmac_f32_e32 v20, v66, v66
	v_fma_f32 v19, v39, v68, v19
	v_add_f32_e32 v69, v16, v17
	v_and_b32_e32 v17, 0xffff0000, v47
	v_and_b32_e32 v16, 0xffff0000, v43
	v_fmac_f32_e32 v71, v61, v61
	v_fmac_f32_e32 v20, v67, v67
	v_add_f32_e32 v68, v18, v19
	v_pk_mul_f32 v[16:17], v[48:49], v[16:17]
	v_fmac_f32_e32 v71, v62, v62
	v_fmac_f32_e32 v20, v68, v68
	v_fma_f32 v17, v39, v70, v17
	v_fmac_f32_e32 v20, v69, v69
	v_fmac_f32_e32 v71, v63, v63
	v_add_f32_e32 v39, v16, v17
	v_fmac_f32_e32 v20, v39, v39
	v_fmac_f32_e32 v71, v64, v64
	s_lshl_b64 s[0:1], s[6:7], 10
	v_lshl_add_u64 v[40:41], v[26:27], 0, s[14:15]
	v_lshl_add_u64 v[42:43], v[26:27], 0, s[0:1]
	s_nop 1
	v_add_f32_dpp v16, v20, v20 quad_perm:[1,0,3,2] row_mask:0xf bank_mask:0xf
	s_nop 1
	v_add_f32_dpp v17, v71, v71 quad_perm:[1,0,3,2] row_mask:0xf bank_mask:0xf
	v_lshl_add_u64 v[48:49], v[26:27], 0, s[10:11]
	v_lshl_add_u64 v[50:51], v[28:29], 0, s[14:15]
	s_lshl_b64 s[6:7], s[2:3], 11
	s_nop 1
	v_add_f32_dpp v16, v16, v16 quad_perm:[2,3,0,1] row_mask:0xf bank_mask:0xf
	s_nop 1
	v_add_f32_dpp v17, v17, v17 quad_perm:[2,3,0,1] row_mask:0xf bank_mask:0xf
	s_cmpk_gt_i32 s4, 0x7fff
	s_nop 1
	v_add_f32_dpp v44, v16, v16 row_half_mirror row_mask:0xf bank_mask:0xf
	s_nop 1
	v_add_f32_dpp v46, v17, v17 row_half_mirror row_mask:0xf bank_mask:0xf
; DI unsigned pk2(float lo, float hi) { return pg8::cvt_pk_bf16(lo, hi); }
; __global__ void __launch_bounds__(512, 2) fwd_megakernel(Params P) {
;     ...
;     for (int m = gw; m < T; m += 2 * NGW) {
;         float l[2][3]; u32x4 r0[2], r1[2], r2[2], rb_[2];
; #pragma unroll
;         for (int j = 0; j < 2; ++j) { const int mj = (m + j * NGW < T) ? m + j * NGW : m;
;             l[j][0] = LSE[(size_t)mj * 8 + h]; l[j][1] = LSE[(size_t)(T + mj) * 8 + h]; l[j][2] = LSE[(size_t)(2 * T + mj) * 8 + h];
;             r0[j] = *(const u32x4*)(OA + (size_t)mj * 512 + 8 * lane); r1[j] = *(const u32x4*)(OA + (size_t)(T + mj) * 512 + 8 * lane); r2[j] = *(const u32x4*)(OA + (size_t)(2 * T + mj) * 512 + 8 * lane);
;             rb_[j] = *(const u32x4*)(OB + (size_t)mj * 512 + 8 * lane); }
; #pragma unroll
;         for (int j = 0; j < 2; ++j) { const int mj = m + j * NGW;
;             const float mx = fmaxf(l[j][0], fmaxf(l[j][1], l[j][2])); float w0 = __expf(l[j][0] - mx), w1 = __expf(l[j][1] - mx), w2 = __expf(l[j][2] - mx); const float inv = 1.f / (w0 + w1 + w2); w0 *= inv; w1 *= inv; w2 *= inv;
;             float a0[8], a1[8], a2[8], ob[8], oa[8];
;             unpack8(r0[j], a0); unpack8(r1[j], a1); unpack8(r2[j], a2); unpack8(rb_[j], ob);
;             float sa = 0.f, sb = 0.f;
; #pragma unroll
;             for (int i = 0; i < 8; ++i) { oa[i] = w0 * a0[i] + w1 * a1[i] + w2 * a2[i]; sa += oa[i] * oa[i]; sb += ob[i] * ob[i]; }
;             const float ra = __builtin_amdgcn_rsqf(wave_sum(sa) * (1.f / 512.f) + EPS), rb = __builtin_amdgcn_rsqf(wave_sum(sb) * (1.f / 512.f) + EPS);
;             u32x4 wa, wb;
;             wa.x = pk2(oa[0] * ra * ga0[0], oa[1] * ra * ga0[1]); wa.y = pk2(oa[2] * ra * ga0[2], oa[3] * ra * ga0[3]); wa.z = pk2(oa[4] * ra * ga1[0], oa[5] * ra * ga1[1]); wa.w = pk2(oa[6] * ra * ga1[2], oa[7] * ra * ga1[3]);
;             wb.x = pk2(ob[0] * rb * gb0[0], ob[1] * rb * gb0[1]); wb.y = pk2(ob[2] * rb * gb0[2], ob[3] * rb * gb0[3]); wb.z = pk2(ob[4] * rb * gb1[0], ob[5] * rb * gb1[1]); wb.w = pk2(ob[6] * rb * gb1[2], ob[7] * rb * gb1[3]);
;             if (mj < T) { *(u32x4*)(HB + (size_t)mj * 1024 + 8 * lane) = wa; *(u32x4*)(HB + (size_t)mj * 1024 + 512 + 8 * lane) = wb; } }
	global_load_dwordx4 v[16:19], v[40:41], off
	global_load_dwordx4 v[20:23], v[42:43], off
	s_nop 1
	v_add_f32_dpp v40, v44, v44 row_mirror row_mask:0xf bank_mask:0xf
	s_nop 1
	v_add_f32_dpp v42, v46, v46 row_mirror row_mask:0xf bank_mask:0xf
	v_mov_b32_e32 v41, v40
	v_mov_b32_e32 v43, v42
	s_nop 1
	v_permlane16_swap_b32_e32 v41, v40
	v_add_f32_e32 v70, v40, v41
	s_nop 1
	v_permlane16_swap_b32_e32 v43, v42
	v_add_f32_e32 v72, v42, v43
	global_load_dwordx4 v[40:43], v[48:49], off
	global_load_dwordx4 v[44:47], v[50:51], off
	v_mov_b32_e32 v71, v70
	v_mov_b32_e32 v73, v72
	s_nop 1
	v_permlane32_swap_b32_e32 v71, v70
	v_add_f32_e32 v48, v70, v71
	v_fmamk_f32 v48, v48, 0x3b000000, v38
	v_rsq_f32_e32 v51, v48
	s_nop 1
	v_permlane32_swap_b32_e32 v73, v72
	v_add_f32_e32 v48, v72, v73
	v_fmamk_f32 v48, v48, 0x3b000000, v38
	v_rsq_f32_e32 v70, v48
	v_mul_f32_e32 v48, v54, v51
	v_mul_f32_e32 v49, v55, v51
	v_mul_f32_e32 v48, v4, v48
	v_mul_f32_e32 v49, v5, v49
	v_cvt_pk_bf16_f32 v48, v48, v49
	v_mul_f32_e32 v49, v65, v51
	v_mul_f32_e32 v50, v66, v51
	v_mul_f32_e32 v49, v6, v49
	v_mul_f32_e32 v50, v7, v50
	v_cvt_pk_bf16_f32 v49, v49, v50
	v_mul_f32_e32 v50, v67, v51
	v_mul_f32_e32 v54, v68, v51
	v_mul_f32_e32 v50, v12, v50
	v_mul_f32_e32 v54, v13, v54
	v_mul_f32_e32 v39, v39, v51
	v_cvt_pk_bf16_f32 v50, v50, v54
	v_mul_f32_e32 v54, v69, v51
	v_mul_f32_e32 v39, v15, v39
	v_mul_f32_e32 v54, v14, v54
	v_cvt_pk_bf16_f32 v51, v54, v39
	v_mul_f32_e32 v39, v70, v52
	v_mul_f32_e32 v52, v70, v53
	s_waitcnt vmcnt(4)
	v_max3_f32 v53, v56, v57, v58
	v_sub_f32_e32 v54, v56, v53
	v_sub_f32_e32 v55, v57, v53
	v_mul_f32_e32 v54, 0x3fb8aa3b, v54
	v_mul_f32_e32 v55, 0x3fb8aa3b, v55
	v_sub_f32_e32 v53, v58, v53
	v_exp_f32_e32 v54, v54
	v_exp_f32_e32 v55, v55
	v_mul_f32_e32 v53, 0x3fb8aa3b, v53
	v_exp_f32_e32 v56, v53
	v_mul_f32_e32 v39, v0, v39
	v_add_f32_e32 v57, v54, v55
	v_mul_f32_e32 v52, v1, v52
	v_add_f32_e32 v57, v56, v57
	v_div_scale_f32 v58, s[0:1], v57, v57, 1.0
	v_cvt_pk_bf16_f32 v52, v39, v52
	v_mul_f32_e32 v39, v70, v59
	v_rcp_f32_e32 v59, v58
	v_mul_f32_e32 v53, v70, v60
	v_mul_f32_e32 v39, v2, v39
	v_mul_f32_e32 v53, v3, v53
	v_fma_f32 v60, -v58, v59, 1.0
	v_fmac_f32_e32 v59, v60, v59
	v_div_scale_f32 v60, vcc, 1.0, v57, 1.0
	v_cvt_pk_bf16_f32 v53, v39, v53
	v_mul_f32_e32 v39, v70, v61
	v_mul_f32_e32 v61, v60, v59
	v_fma_f32 v65, -v58, v61, v60
	v_fmac_f32_e32 v61, v65, v59
	v_fma_f32 v58, -v58, v61, v60
	v_div_fmas_f32 v58, v58, v59, v61
	v_div_fixup_f32 v57, v58, v57, 1.0
	v_mul_f32_e32 v55, v55, v57
	s_waitcnt vmcnt(2)
	v_lshlrev_b32_e32 v61, 16, v20
	v_and_b32_e32 v20, 0xffff0000, v20
	v_mul_f32_e32 v54, v54, v57
	v_mul_f32_e32 v56, v56, v57
	v_lshlrev_b32_e32 v57, 16, v16
	v_and_b32_e32 v16, 0xffff0000, v16
	v_mul_f32_e32 v20, v55, v20
	v_lshlrev_b32_e32 v65, 16, v21
	v_and_b32_e32 v21, 0xffff0000, v21
	v_mul_f32_e32 v61, v55, v61
	s_waitcnt vmcnt(1)
	v_lshlrev_b32_e32 v68, 16, v40
	v_and_b32_e32 v40, 0xffff0000, v40
	v_fmac_f32_e32 v20, v54, v16
	v_lshlrev_b32_e32 v58, 16, v17
	v_and_b32_e32 v17, 0xffff0000, v17
	v_fmac_f32_e32 v61, v54, v57
	v_fmac_f32_e32 v20, v56, v40
	v_mul_f32_e32 v57, v55, v65
	v_mul_f32_e32 v21, v55, v21
	v_lshlrev_b32_e32 v66, 16, v22
	v_and_b32_e32 v22, 0xffff0000, v22
	v_lshlrev_b32_e32 v69, 16, v41
	v_and_b32_e32 v41, 0xffff0000, v41
	v_fmac_f32_e32 v61, v56, v68
	v_mul_f32_e32 v16, v20, v20
	v_fmac_f32_e32 v57, v54, v58
	v_fmac_f32_e32 v21, v54, v17
	v_lshlrev_b32_e32 v59, 16, v18
	v_and_b32_e32 v18, 0xffff0000, v18
	v_fmac_f32_e32 v16, v61, v61
	v_fmac_f32_e32 v57, v56, v69
	v_fmac_f32_e32 v21, v56, v41
	v_mul_f32_e32 v41, v55, v66
	v_mul_f32_e32 v22, v55, v22
	v_lshlrev_b32_e32 v67, 16, v23
	v_lshlrev_b32_e32 v71, 16, v42
	v_and_b32_e32 v42, 0xffff0000, v42
	v_fmac_f32_e32 v16, v57, v57
	v_fmac_f32_e32 v41, v54, v59
	v_fmac_f32_e32 v22, v54, v18
	v_lshlrev_b32_e32 v60, 16, v19
	v_and_b32_e32 v23, 0xffff0000, v23
	s_waitcnt vmcnt(0)
; DI unsigned pk2(float lo, float hi) { return pg8::cvt_pk_bf16(lo, hi); }
; __global__ void __launch_bounds__(512, 2) fwd_megakernel(Params P) {
;     ...
;         for (int j = 0; j < 2; ++j) { const int mj = m + j * NGW;
;             const float mx = fmaxf(l[j][0], fmaxf(l[j][1], l[j][2])); float w0 = __expf(l[j][0] - mx), w1 = __expf(l[j][1] - mx), w2 = __expf(l[j][2] - mx); const float inv = 1.f / (w0 + w1 + w2); w0 *= inv; w1 *= inv; w2 *= inv;
;             float a0[8], a1[8], a2[8], ob[8], oa[8];
;             unpack8(r0[j], a0); unpack8(r1[j], a1); unpack8(r2[j], a2); unpack8(rb_[j], ob);
;             float sa = 0.f, sb = 0.f;
; #pragma unroll
;             for (int i = 0; i < 8; ++i) { oa[i] = w0 * a0[i] + w1 * a1[i] + w2 * a2[i]; sa += oa[i] * oa[i]; sb += ob[i] * ob[i]; }
;             const float ra = __builtin_amdgcn_rsqf(wave_sum(sa) * (1.f / 512.f) + EPS), rb = __builtin_amdgcn_rsqf(wave_sum(sb) * (1.f / 512.f) + EPS);
;             u32x4 wa, wb;
;             wa.x = pk2(oa[0] * ra * ga0[0], oa[1] * ra * ga0[1]); wa.y = pk2(oa[2] * ra * ga0[2], oa[3] * ra * ga0[3]); wa.z = pk2(oa[4] * ra * ga1[0], oa[5] * ra * ga1[1]); wa.w = pk2(oa[6] * ra * ga1[2], oa[7] * ra * ga1[3]);
;             wb.x = pk2(ob[0] * rb * gb0[0], ob[1] * rb * gb0[1]); wb.y = pk2(ob[2] * rb * gb0[2], ob[3] * rb * gb0[3]); wb.z = pk2(ob[4] * rb * gb1[0], ob[5] * rb * gb1[1]); wb.w = pk2(ob[6] * rb * gb1[2], ob[7] * rb * gb1[3]);
;             if (mj < T) { *(u32x4*)(HB + (size_t)mj * 1024 + 8 * lane) = wa; *(u32x4*)(HB + (size_t)mj * 1024 + 512 + 8 * lane) = wb; } }
	v_lshlrev_b32_e32 v73, 16, v44
	v_and_b32_e32 v44, 0xffff0000, v44
	v_fmac_f32_e32 v16, v21, v21
	v_fmac_f32_e32 v41, v56, v71
	v_fmac_f32_e32 v22, v56, v42
	v_mul_f32_e32 v42, v55, v67
	v_and_b32_e32 v19, 0xffff0000, v19
	v_lshlrev_b32_e32 v72, 16, v43
	v_mul_f32_e32 v40, v44, v44
	v_fmac_f32_e32 v16, v41, v41
	v_fmac_f32_e32 v42, v54, v60
	v_mul_f32_e32 v23, v55, v23
	v_and_b32_e32 v43, 0xffff0000, v43
	v_lshlrev_b32_e32 v74, 16, v45
	v_fmac_f32_e32 v40, v73, v73
	v_fmac_f32_e32 v16, v22, v22
	v_fmac_f32_e32 v42, v56, v72
	v_fmac_f32_e32 v23, v54, v19
	v_and_b32_e32 v45, 0xffff0000, v45
	v_fmac_f32_e32 v40, v74, v74
	v_fmac_f32_e32 v16, v42, v42
	v_fmac_f32_e32 v23, v56, v43
	v_lshlrev_b32_e32 v75, 16, v46
	v_fmac_f32_e32 v40, v45, v45
	v_fmac_f32_e32 v16, v23, v23
	v_and_b32_e32 v46, 0xffff0000, v46
	v_fmac_f32_e32 v40, v75, v75
	v_lshlrev_b32_e32 v76, 16, v47
	v_fmac_f32_e32 v40, v46, v46
	v_and_b32_e32 v47, 0xffff0000, v47
	v_fmac_f32_e32 v40, v76, v76
	v_fmac_f32_e32 v40, v47, v47
	s_nop 1
	v_add_f32_dpp v16, v16, v16 quad_perm:[1,0,3,2] row_mask:0xf bank_mask:0xf
	v_mul_f32_e32 v39, v8, v39
	v_mul_f32_e32 v19, v70, v62
	s_nop 1
	v_add_f32_dpp v18, v40, v40 quad_perm:[1,0,3,2] row_mask:0xf bank_mask:0xf
	s_nop 1
	v_add_f32_dpp v16, v16, v16 quad_perm:[2,3,0,1] row_mask:0xf bank_mask:0xf
	v_mul_f32_e32 v19, v9, v19
	v_cvt_pk_bf16_f32 v54, v39, v19
	s_nop 1
	v_add_f32_dpp v18, v18, v18 quad_perm:[2,3,0,1] row_mask:0xf bank_mask:0xf
	s_nop 1
	v_add_f32_dpp v16, v16, v16 row_half_mirror row_mask:0xf bank_mask:0xf
	v_mul_f32_e32 v19, v70, v63
	v_mul_f32_e32 v19, v10, v19
	s_nop 1
	v_add_f32_dpp v18, v18, v18 row_half_mirror row_mask:0xf bank_mask:0xf
	s_nop 1
	v_add_f32_dpp v43, v16, v16 row_mirror row_mask:0xf bank_mask:0xf
	v_mov_b32_e32 v56, v43
	v_mul_f32_e32 v40, v70, v64
	v_mul_f32_e32 v40, v11, v40
	s_nop 1
	v_add_f32_dpp v18, v18, v18 row_mirror row_mask:0xf bank_mask:0xf
	v_cvt_pk_bf16_f32 v55, v19, v40
	v_mov_b32_e32 v19, v18
	s_nop 1
	v_permlane16_swap_b32_e32 v56, v43
	v_add_f32_e32 v39, v43, v56
	v_mov_b32_e32 v40, v39
	v_lshl_add_u64 v[16:17], v[30:31], 0, s[6:7]
	global_store_dwordx4 v[16:17], v[48:51], off
	s_nop 1
	v_permlane16_swap_b32_e32 v19, v18
	v_add_f32_e32 v18, v18, v19
	v_mov_b32_e32 v19, v18
	global_store_dwordx4 v[16:17], v[52:55], off offset:1024
	s_nop 1
	v_permlane32_swap_b32_e32 v40, v39
	v_add_f32_e32 v16, v39, v40
	v_fmamk_f32 v16, v16, 0x3b000000, v38
	v_rsq_f32_e32 v39, v16
	s_nop 1
	v_permlane32_swap_b32_e32 v19, v18
	v_add_f32_e32 v16, v18, v19
	v_fmamk_f32 v16, v16, 0x3b000000, v38
	v_rsq_f32_e32 v40, v16
	v_mul_f32_e32 v16, v61, v39
	v_mul_f32_e32 v17, v20, v39
	v_mul_f32_e32 v16, v4, v16
	v_mul_f32_e32 v17, v5, v17
	v_cvt_pk_bf16_f32 v16, v16, v17
	v_mul_f32_e32 v17, v57, v39
	v_mul_f32_e32 v18, v21, v39
	v_mul_f32_e32 v17, v6, v17
	v_mul_f32_e32 v18, v7, v18
	v_cvt_pk_bf16_f32 v17, v17, v18
	v_mul_f32_e32 v18, v41, v39
	v_mul_f32_e32 v19, v22, v39
	v_mul_f32_e32 v18, v12, v18
	v_mul_f32_e32 v19, v13, v19
	v_cvt_pk_bf16_f32 v18, v18, v19
	v_mul_f32_e32 v19, v42, v39
	v_mul_f32_e32 v20, v23, v39
	v_mul_f32_e32 v19, v14, v19
	v_mul_f32_e32 v20, v15, v20
	v_cvt_pk_bf16_f32 v19, v19, v20
	v_mul_f32_e32 v20, v40, v73
	v_mul_f32_e32 v21, v40, v44
	v_mul_f32_e32 v20, v0, v20
	v_mul_f32_e32 v21, v1, v21
	v_cvt_pk_bf16_f32 v20, v20, v21
	v_mul_f32_e32 v21, v40, v74
	v_mul_f32_e32 v22, v40, v45
	v_mul_f32_e32 v21, v2, v21
	v_mul_f32_e32 v22, v3, v22
	v_cvt_pk_bf16_f32 v21, v21, v22
	v_mul_f32_e32 v22, v40, v75
	v_mul_f32_e32 v23, v40, v46
	v_mul_f32_e32 v22, v8, v22
	v_mul_f32_e32 v23, v9, v23
	v_cvt_pk_bf16_f32 v22, v22, v23
	v_mul_f32_e32 v23, v40, v76
	v_mul_f32_e32 v23, v10, v23
	v_mul_f32_e32 v39, v40, v47
	v_mul_f32_e32 v39, v11, v39
	v_cvt_pk_bf16_f32 v23, v23, v39
	s_cbranch_scc1 .LBB0_992
	s_ashr_i32 s5, s4, 31
	s_lshl_b64 s[0:1], s[4:5], 11
	v_lshl_add_u64 v[40:41], v[30:31], 0, s[0:1]
	global_store_dwordx4 v[40:41], v[16:19], off
	global_store_dwordx4 v[40:41], v[20:23], off offset:1024
	s_branch .LBB0_992
